# norm-phase GEMV loops and forget-weight setup as compact loops with 16/4 loads in flight; prologue transposes with 32 loads in flight
# speedup vs baseline: 1.0007x; 1.0006x over previous
; __device__ __forceinline__ unsigned pk2(float lo, float hi) { unsigned r; asm volatile("v_cvt_pk_bf16_f32 %0, %1, %2" : "=v"(r) : "v"(lo), "v"(hi)); return r; }
; __device__ __forceinline__ void norm_phase(const float* src, const float* gain, const float* shp, const float* scp, bf16* XN,
;                                            const float* w_in, const float* b_f, float* LF, LAS unsigned char* lds, int tid, int lane, int wave, int gw, int ngw) {
;     ...
;     for (int idx = tid; idx < 8192; idx += NTHREADS) { const int k = idx >> 2, n4 = idx & 3;
;         const f32x4 v = *(const f32x4*)(w_in + (size_t)k * NIN + 3 * DM + 4 * n4);
; #pragma unroll
;         for (int i = 0; i < 4; ++i) { const unsigned hb = pk2(v[i], 0.f) & 0xffffu; const unsigned lb = pk2(v[i] - __uint_as_float(hb << 16), 0.f) & 0xffffu;
;             WFT[(4 * n4 + i) * WFT_LD + k] = (bf16)hb; WFT[(16 + 4 * n4 + i) * WFT_LD + k] = (bf16)lb; } }
.LBB0_559:
	v_ashrrev_i32_e32 v6, 2, v1
	v_mov_b64_e32 v[2:3], s[40:41]
	v_and_b32_e32 v7, 12, v0
	v_mad_i64_i32 v[2:3], s[20:21], v6, s91, v[2:3]
	v_lshlrev_b32_e32 v194, 2, v7
	v_lshl_add_u64 v[2:3], v[2:3], 0, v[194:195]
	v_add_co_u32_e32 v2, vcc, 0x6000, v2
	v_mul_u32_u24_e32 v7, 0x1010, v7
	s_nop 0
	v_addc_co_u32_e32 v3, vcc, 0, v3, vcc
	v_lshlrev_b32_e32 v6, 1, v6
	v_add3_u32 v6, 0, v7, v6
	v_add_u32_e32 v7, 0x10100, v6
	s_mov_b32 s18, 0x302000
	s_mov_b32 s19, 0
	s_mov_b32 s20, 0
.Lwft_loop:
	global_load_dwordx4 v[32:35], v[2:3], off
	v_lshl_add_u64 v[2:3], v[2:3], 0, s[18:19]
	global_load_dwordx4 v[36:39], v[2:3], off
	v_lshl_add_u64 v[2:3], v[2:3], 0, s[18:19]
	global_load_dwordx4 v[40:43], v[2:3], off
	v_lshl_add_u64 v[2:3], v[2:3], 0, s[18:19]
	global_load_dwordx4 v[44:47], v[2:3], off
	v_lshl_add_u64 v[2:3], v[2:3], 0, s[18:19]
	s_waitcnt vmcnt(3)
	v_cvt_pk_bf16_f32 v11, v32, v195
	s_nop 0
	v_lshlrev_b32_e32 v12, 16, v11
	v_sub_f32_e32 v32, v32, v12
	v_cvt_pk_bf16_f32 v32, v32, v195
	s_nop 0
	ds_write_b16 v6, v11
	ds_write_b16 v7, v32
	v_cvt_pk_bf16_f32 v11, v33, v195
	s_nop 0
	v_lshlrev_b32_e32 v12, 16, v11
	v_sub_f32_e32 v33, v33, v12
	v_cvt_pk_bf16_f32 v33, v33, v195
	s_nop 0
	ds_write_b16 v6, v11 offset:4112
	ds_write_b16 v7, v33 offset:4112
	v_cvt_pk_bf16_f32 v11, v34, v195
	s_nop 0
	v_lshlrev_b32_e32 v12, 16, v11
	v_sub_f32_e32 v34, v34, v12
	v_cvt_pk_bf16_f32 v34, v34, v195
	s_nop 0
	ds_write_b16 v6, v11 offset:8224
	ds_write_b16 v7, v34 offset:8224
	v_cvt_pk_bf16_f32 v11, v35, v195
	s_nop 0
	v_lshlrev_b32_e32 v12, 16, v11
	v_sub_f32_e32 v35, v35, v12
	v_cvt_pk_bf16_f32 v35, v35, v195
	s_nop 0
	ds_write_b16 v6, v11 offset:12336
	ds_write_b16 v7, v35 offset:12336
	s_waitcnt vmcnt(2)
	v_cvt_pk_bf16_f32 v11, v36, v195
	s_nop 0
	v_lshlrev_b32_e32 v12, 16, v11
	v_sub_f32_e32 v36, v36, v12
	v_cvt_pk_bf16_f32 v36, v36, v195
	s_nop 0
	ds_write_b16 v6, v11 offset:256
	ds_write_b16 v7, v36 offset:256
	v_cvt_pk_bf16_f32 v11, v37, v195
	s_nop 0
	v_lshlrev_b32_e32 v12, 16, v11
	v_sub_f32_e32 v37, v37, v12
	v_cvt_pk_bf16_f32 v37, v37, v195
	s_nop 0
	ds_write_b16 v6, v11 offset:4368
	ds_write_b16 v7, v37 offset:4368
	v_cvt_pk_bf16_f32 v11, v38, v195
	s_nop 0
	v_lshlrev_b32_e32 v12, 16, v11
	v_sub_f32_e32 v38, v38, v12
	v_cvt_pk_bf16_f32 v38, v38, v195
	s_nop 0
	ds_write_b16 v6, v11 offset:8480
	ds_write_b16 v7, v38 offset:8480
	v_cvt_pk_bf16_f32 v11, v39, v195
	s_nop 0
	v_lshlrev_b32_e32 v12, 16, v11
	v_sub_f32_e32 v39, v39, v12
	v_cvt_pk_bf16_f32 v39, v39, v195
	s_nop 0
	ds_write_b16 v6, v11 offset:12592
	ds_write_b16 v7, v39 offset:12592
	s_waitcnt vmcnt(1)
	v_cvt_pk_bf16_f32 v11, v40, v195
	s_nop 0
	v_lshlrev_b32_e32 v12, 16, v11
	v_sub_f32_e32 v40, v40, v12
	v_cvt_pk_bf16_f32 v40, v40, v195
	s_nop 0
	ds_write_b16 v6, v11 offset:512
	ds_write_b16 v7, v40 offset:512
	v_cvt_pk_bf16_f32 v11, v41, v195
	s_nop 0
	v_lshlrev_b32_e32 v12, 16, v11
	v_sub_f32_e32 v41, v41, v12
	v_cvt_pk_bf16_f32 v41, v41, v195
	s_nop 0
	ds_write_b16 v6, v11 offset:4624
	ds_write_b16 v7, v41 offset:4624
	v_cvt_pk_bf16_f32 v11, v42, v195
	s_nop 0
	v_lshlrev_b32_e32 v12, 16, v11
	v_sub_f32_e32 v42, v42, v12
	v_cvt_pk_bf16_f32 v42, v42, v195
	s_nop 0
	ds_write_b16 v6, v11 offset:8736
	ds_write_b16 v7, v42 offset:8736
	v_cvt_pk_bf16_f32 v11, v43, v195
	s_nop 0
	v_lshlrev_b32_e32 v12, 16, v11
	v_sub_f32_e32 v43, v43, v12
	v_cvt_pk_bf16_f32 v43, v43, v195
	s_nop 0
	ds_write_b16 v6, v11 offset:12848
	ds_write_b16 v7, v43 offset:12848
	s_waitcnt vmcnt(0)
	v_cvt_pk_bf16_f32 v11, v44, v195
	s_nop 0
	v_lshlrev_b32_e32 v12, 16, v11
	v_sub_f32_e32 v44, v44, v12
	v_cvt_pk_bf16_f32 v44, v44, v195
	s_nop 0
	ds_write_b16 v6, v11 offset:768
	ds_write_b16 v7, v44 offset:768
	v_cvt_pk_bf16_f32 v11, v45, v195
	s_nop 0
	v_lshlrev_b32_e32 v12, 16, v11
	v_sub_f32_e32 v45, v45, v12
	v_cvt_pk_bf16_f32 v45, v45, v195
	s_nop 0
	ds_write_b16 v6, v11 offset:4880
	ds_write_b16 v7, v45 offset:4880
	v_cvt_pk_bf16_f32 v11, v46, v195
	s_nop 0
	v_lshlrev_b32_e32 v12, 16, v11
	v_sub_f32_e32 v46, v46, v12
	v_cvt_pk_bf16_f32 v46, v46, v195
	s_nop 0
	ds_write_b16 v6, v11 offset:8992
	ds_write_b16 v7, v46 offset:8992
	v_cvt_pk_bf16_f32 v11, v47, v195
	s_nop 0
	v_lshlrev_b32_e32 v12, 16, v11
	v_sub_f32_e32 v47, v47, v12
	v_cvt_pk_bf16_f32 v47, v47, v195
	s_nop 0
	ds_write_b16 v6, v11 offset:13104
	ds_write_b16 v7, v47 offset:13104
	v_add_u32_e32 v6, 0x400, v6
	v_add_u32_e32 v7, 0x400, v7
	s_add_i32 s20, s20, 1
	s_cmp_lg_u32 s20, 4
	s_cbranch_scc1 .Lwft_loop

; #define LAS __attribute__((address_space(3)))
; __device__ __forceinline__ void norm_phase(const float* src, const float* gain, const float* shp, const float* scp, bf16* XN,
;                                            const float* w_in, const float* b_f, float* LF, LAS unsigned char* lds, int tid, int lane, int wave, int gw, int ngw) {
;     ...
;             const bf16* xp = XN + (size_t)(row0 + fr) * DM + 8 * fq;
;             const LAS bf16* yh = WFT + fr * WFT_LD + 8 * fq; const LAS bf16* yl = yh + 16 * WFT_LD;
;             pg8::f32x4 ah = {0.f, 0.f, 0.f, 0.f}, al = {0.f, 0.f, 0.f, 0.f};
; #pragma unroll 8
;             for (int kk = 0; kk < DM / 32; ++kk) { const pg8::bf16x8 xf = *(const pg8::bf16x8*)(xp + 32 * kk);
;                 ah = __builtin_amdgcn_mfma_f32_16x16x32_bf16(xf, *(const LAS pg8::bf16x8*)(yh + 32 * kk), ah, 0, 0, 0);
;                 al = __builtin_amdgcn_mfma_f32_16x16x32_bf16(xf, *(const LAS pg8::bf16x8*)(yl + 32 * kk), al, 0, 0, 0); }
.LBB0_566:
	v_mov_b32_e32 v188, v21
	v_add_u32_e32 v189, 0x10100, v21
	global_load_dwordx4 v[64:67], v[18:19], off offset:-448
	global_load_dwordx4 v[68:71], v[18:19], off offset:-384
	global_load_dwordx4 v[72:75], v[18:19], off offset:-320
	global_load_dwordx4 v[76:79], v[18:19], off offset:-256
	global_load_dwordx4 v[80:83], v[18:19], off offset:-192
	global_load_dwordx4 v[84:87], v[18:19], off offset:-128
	global_load_dwordx4 v[88:91], v[18:19], off offset:-64
	global_load_dwordx4 v[92:95], v[18:19], off offset:0
	global_load_dwordx4 v[96:99], v[18:19], off offset:64
	global_load_dwordx4 v[100:103], v[18:19], off offset:128
	global_load_dwordx4 v[104:107], v[18:19], off offset:192
	global_load_dwordx4 v[108:111], v[18:19], off offset:256
	global_load_dwordx4 v[112:115], v[18:19], off offset:320
	global_load_dwordx4 v[116:119], v[18:19], off offset:384
	global_load_dwordx4 v[120:123], v[18:19], off offset:448
	global_load_dwordx4 v[124:127], v[18:19], off offset:512
	ds_read_b128 v[172:175], v188
	ds_read_b128 v[176:179], v189
	s_mov_b64 s[14:15], 0x400
	s_mov_b32 s7, 0
.Llogit_loop:
	ds_read_b128 v[180:183], v188 offset:64
	ds_read_b128 v[184:187], v189 offset:64
	s_waitcnt vmcnt(15) lgkmcnt(2)
	v_mfma_f32_16x16x32_bf16 v[0:3], v[64:67], v[172:175], v[0:3]
	v_mfma_f32_16x16x32_bf16 v[4:7], v[64:67], v[176:179], v[4:7]
	ds_read_b128 v[172:175], v188 offset:128
	ds_read_b128 v[176:179], v189 offset:128
	s_waitcnt vmcnt(14) lgkmcnt(2)
	v_mfma_f32_16x16x32_bf16 v[0:3], v[68:71], v[180:183], v[0:3]
	v_mfma_f32_16x16x32_bf16 v[4:7], v[68:71], v[184:187], v[4:7]
	global_load_dwordx4 v[64:67], v[18:19], off offset:576
	ds_read_b128 v[180:183], v188 offset:192
	ds_read_b128 v[184:187], v189 offset:192
	s_waitcnt vmcnt(14) lgkmcnt(2)
	v_mfma_f32_16x16x32_bf16 v[0:3], v[72:75], v[172:175], v[0:3]
	v_mfma_f32_16x16x32_bf16 v[4:7], v[72:75], v[176:179], v[4:7]
	global_load_dwordx4 v[68:71], v[18:19], off offset:640
	ds_read_b128 v[172:175], v188 offset:256
	ds_read_b128 v[176:179], v189 offset:256
	s_waitcnt vmcnt(14) lgkmcnt(2)
	v_mfma_f32_16x16x32_bf16 v[0:3], v[76:79], v[180:183], v[0:3]
	v_mfma_f32_16x16x32_bf16 v[4:7], v[76:79], v[184:187], v[4:7]
	global_load_dwordx4 v[72:75], v[18:19], off offset:704
	ds_read_b128 v[180:183], v188 offset:320
	ds_read_b128 v[184:187], v189 offset:320
	s_waitcnt vmcnt(14) lgkmcnt(2)
	v_mfma_f32_16x16x32_bf16 v[0:3], v[80:83], v[172:175], v[0:3]
	v_mfma_f32_16x16x32_bf16 v[4:7], v[80:83], v[176:179], v[4:7]
	global_load_dwordx4 v[76:79], v[18:19], off offset:768
	ds_read_b128 v[172:175], v188 offset:384
	ds_read_b128 v[176:179], v189 offset:384
	s_waitcnt vmcnt(14) lgkmcnt(2)
	v_mfma_f32_16x16x32_bf16 v[0:3], v[84:87], v[180:183], v[0:3]
	v_mfma_f32_16x16x32_bf16 v[4:7], v[84:87], v[184:187], v[4:7]
	global_load_dwordx4 v[80:83], v[18:19], off offset:832
	ds_read_b128 v[180:183], v188 offset:448
	ds_read_b128 v[184:187], v189 offset:448
	s_waitcnt vmcnt(14) lgkmcnt(2)
	v_mfma_f32_16x16x32_bf16 v[0:3], v[88:91], v[172:175], v[0:3]
	v_mfma_f32_16x16x32_bf16 v[4:7], v[88:91], v[176:179], v[4:7]
	global_load_dwordx4 v[84:87], v[18:19], off offset:896
	ds_read_b128 v[172:175], v188 offset:512
	ds_read_b128 v[176:179], v189 offset:512
	s_waitcnt vmcnt(14) lgkmcnt(2)
	v_mfma_f32_16x16x32_bf16 v[0:3], v[92:95], v[180:183], v[0:3]
	v_mfma_f32_16x16x32_bf16 v[4:7], v[92:95], v[184:187], v[4:7]
	global_load_dwordx4 v[88:91], v[18:19], off offset:960
	ds_read_b128 v[180:183], v188 offset:576
	ds_read_b128 v[184:187], v189 offset:576
	s_waitcnt vmcnt(14) lgkmcnt(2)
	v_mfma_f32_16x16x32_bf16 v[0:3], v[96:99], v[172:175], v[0:3]
	v_mfma_f32_16x16x32_bf16 v[4:7], v[96:99], v[176:179], v[4:7]
	global_load_dwordx4 v[92:95], v[18:19], off offset:1024
	ds_read_b128 v[172:175], v188 offset:640
	ds_read_b128 v[176:179], v189 offset:640
	s_waitcnt vmcnt(14) lgkmcnt(2)
	v_mfma_f32_16x16x32_bf16 v[0:3], v[100:103], v[180:183], v[0:3]
	v_mfma_f32_16x16x32_bf16 v[4:7], v[100:103], v[184:187], v[4:7]
	global_load_dwordx4 v[96:99], v[18:19], off offset:1088
	ds_read_b128 v[180:183], v188 offset:704
	ds_read_b128 v[184:187], v189 offset:704
	s_waitcnt vmcnt(14) lgkmcnt(2)
	v_mfma_f32_16x16x32_bf16 v[0:3], v[104:107], v[172:175], v[0:3]
	v_mfma_f32_16x16x32_bf16 v[4:7], v[104:107], v[176:179], v[4:7]
	global_load_dwordx4 v[100:103], v[18:19], off offset:1152
	ds_read_b128 v[172:175], v188 offset:768
	ds_read_b128 v[176:179], v189 offset:768
	s_waitcnt vmcnt(14) lgkmcnt(2)
	v_mfma_f32_16x16x32_bf16 v[0:3], v[108:111], v[180:183], v[0:3]
	v_mfma_f32_16x16x32_bf16 v[4:7], v[108:111], v[184:187], v[4:7]
	global_load_dwordx4 v[104:107], v[18:19], off offset:1216
	ds_read_b128 v[180:183], v188 offset:832
	ds_read_b128 v[184:187], v189 offset:832
	s_waitcnt vmcnt(14) lgkmcnt(2)
	v_mfma_f32_16x16x32_bf16 v[0:3], v[112:115], v[172:175], v[0:3]
	v_mfma_f32_16x16x32_bf16 v[4:7], v[112:115], v[176:179], v[4:7]
	global_load_dwordx4 v[108:111], v[18:19], off offset:1280
	ds_read_b128 v[172:175], v188 offset:896
	ds_read_b128 v[176:179], v189 offset:896
	s_waitcnt vmcnt(14) lgkmcnt(2)
	v_mfma_f32_16x16x32_bf16 v[0:3], v[116:119], v[180:183], v[0:3]
	v_mfma_f32_16x16x32_bf16 v[4:7], v[116:119], v[184:187], v[4:7]
	global_load_dwordx4 v[112:115], v[18:19], off offset:1344
	ds_read_b128 v[180:183], v188 offset:960
	ds_read_b128 v[184:187], v189 offset:960
	s_waitcnt vmcnt(14) lgkmcnt(2)
	v_mfma_f32_16x16x32_bf16 v[0:3], v[120:123], v[172:175], v[0:3]
	v_mfma_f32_16x16x32_bf16 v[4:7], v[120:123], v[176:179], v[4:7]
	global_load_dwordx4 v[116:119], v[18:19], off offset:1408
	ds_read_b128 v[172:175], v188 offset:1024
	ds_read_b128 v[176:179], v189 offset:1024
	s_waitcnt vmcnt(14) lgkmcnt(2)
	v_mfma_f32_16x16x32_bf16 v[0:3], v[124:127], v[180:183], v[0:3]
	v_mfma_f32_16x16x32_bf16 v[4:7], v[124:127], v[184:187], v[4:7]
	global_load_dwordx4 v[120:123], v[18:19], off offset:1472
	global_load_dwordx4 v[124:127], v[18:19], off offset:1536
	v_add_u32_e32 v188, 0x400, v188
	v_add_u32_e32 v189, 0x400, v189
	v_lshl_add_u64 v[18:19], v[18:19], 0, s[14:15]
	s_add_i32 s7, s7, 1
	s_cmp_lg_u32 s7, 4
	s_cbranch_scc1 .Llogit_loop
; __device__ __forceinline__ void norm_phase(const float* src, const float* gain, const float* shp, const float* scp, bf16* XN,
;                                            const float* w_in, const float* b_f, float* LF, LAS unsigned char* lds, int tid, int lane, int wave, int gw, int ngw) {
;     ...
;             const float bias = b_f[fr]; pg8::f32x4 lf;
; #pragma unroll
;             for (int i = 0; i < 4; ++i) { const float z = ah[i] + al[i] + bias; lf[i] = fminf(z, 0.f) - log1pf(expf(-fabsf(z))); }
	s_nop 1
	global_load_dword v9, v[12:13], off
	s_nop 5
	v_add_f32_e32 v0, v0, v4
	v_add_f32_e32 v1, v1, v5
	s_lshl_b32 s7, s2, 3
	s_mov_b32 s14, 0xb102e308
	s_mov_b32 s8, 0x3ecc95a3
	v_mov_b64_e32 v[4:5], s[8:9]
	s_mov_b32 s8, 0x3e9b6dac
	s_mov_b32 s12, 0x3f2aaada
	v_add_f32_e32 v2, v2, v6
	v_add_f32_e32 v3, v3, v7
	v_add_u32_e32 v16, s85, v16
	s_waitcnt vmcnt(0)
	v_add_f32_e32 v17, v0, v9
	v_add_f32_e32 v18, v1, v9
	v_mul_f32_e64 v0, |v17|, s84
	v_mul_f32_e64 v1, |v18|, s84
	v_fma_f32 v19, |v17|, s84, -v0
	v_rndne_f32_e32 v22, v0
	v_fma_f32 v23, |v18|, s84, -v1
	v_rndne_f32_e32 v24, v1
	v_fma_f32 v19, |v17|, s82, v19
	v_sub_f32_e32 v0, v0, v22
	v_fma_f32 v23, |v18|, s82, v23
	v_sub_f32_e32 v1, v1, v24
	v_add_f32_e32 v0, v0, v19
	v_cvt_i32_f32_e32 v22, v22
	v_add_f32_e32 v1, v1, v23
	v_exp_f32_e32 v19, v0
	v_cvt_i32_f32_e32 v24, v24
	v_exp_f32_e32 v23, v1
	v_cmp_ngt_f32_e64 vcc, |v17|, s83
	v_ldexp_f32 v19, v19, v22
	v_min_f32_e32 v0, 0, v17
	v_ldexp_f32 v22, v23, v24
	v_cndmask_b32_e32 v19, 0, v19, vcc
	v_cmp_ngt_f32_e64 vcc, |v18|, s83
	v_min_f32_e32 v1, 0, v18
	v_add_f32_e32 v6, v2, v9
	v_cndmask_b32_e32 v22, 0, v22, vcc
	v_cmp_nlt_f32_e64 vcc, |v17|, s96
	v_mul_f32_e64 v2, |v6|, s84
	v_add_f32_e32 v9, v3, v9
	v_cndmask_b32_e32 v17, v214, v19, vcc
	v_cmp_nlt_f32_e64 vcc, |v18|, s96
	v_add_f32_e32 v24, 1.0, v17
	v_add_f32_e32 v26, -1.0, v24
	v_cndmask_b32_e32 v50, v214, v22, vcc
	v_add_f32_e32 v25, 1.0, v50
	v_frexp_mant_f32_e32 v29, v25
	v_cvt_f64_f32_e32 v[22:23], v25
	v_frexp_exp_i32_f64_e32 v22, v[22:23]
	v_cmp_gt_f32_e32 vcc, s68, v29
	v_frexp_mant_f32_e32 v27, v24
	v_cvt_f64_f32_e32 v[18:19], v24
	v_add_f32_e32 v28, -1.0, v25
	v_subbrev_co_u32_e32 v22, vcc, 0, v22, vcc
	v_sub_f32_e32 v30, v26, v24
	v_frexp_exp_i32_f64_e32 v18, v[18:19]
	v_sub_f32_e32 v19, v28, v25
	v_cmp_gt_f32_e32 vcc, s68, v27
	v_sub_f32_e32 v26, v17, v26
	v_sub_f32_e32 v28, v50, v28
	v_add_f32_e32 v23, 1.0, v30
	v_add_f32_e32 v19, 1.0, v19
	v_subbrev_co_u32_e32 v18, vcc, 0, v18, vcc
	v_add_f32_e32 v23, v26, v23
	v_add_f32_e32 v26, v28, v19
	v_sub_u32_e32 v27, 0, v18
	v_sub_u32_e32 v28, 0, v22
	v_cvt_f32_i32_e32 v19, v22
	v_cvt_f32_i32_e32 v18, v18
	v_ldexp_f32 v22, v24, v27
	v_ldexp_f32 v24, v23, v27
	v_ldexp_f32 v23, v25, v28
	v_ldexp_f32 v25, v26, v28
	v_pk_add_f32 v[26:27], v[22:23], 1.0 op_sel_hi:[1,0]
	v_pk_add_f32 v[28:29], v[22:23], -1.0 op_sel_hi:[1,0]
	v_pk_add_f32 v[30:31], v[26:27], -1.0 op_sel_hi:[1,0]
	v_pk_add_f32 v[32:33], v[28:29], 1.0 op_sel_hi:[1,0]
	v_pk_add_f32 v[30:31], v[22:23], v[30:31] neg_lo:[0,1] neg_hi:[0,1]
	v_pk_add_f32 v[22:23], v[22:23], v[32:33] neg_lo:[0,1] neg_hi:[0,1]
	v_pk_mul_f32 v[32:33], v[18:19], s[6:7] op_sel_hi:[1,0]
	v_pk_add_f32 v[30:31], v[24:25], v[30:31]
	v_pk_add_f32 v[22:23], v[24:25], v[22:23]
	v_pk_fma_f32 v[24:25], v[18:19], s[6:7], v[32:33] op_sel_hi:[1,0,1] neg_lo:[0,0,1] neg_hi:[0,0,1]
	v_pk_add_f32 v[36:37], v[26:27], v[30:31]
	v_pk_fma_f32 v[18:19], v[18:19], s[14:15], v[24:25] op_sel_hi:[1,0,1]
	v_rcp_f32_e32 v24, v36
	v_rcp_f32_e32 v25, v37
	v_pk_add_f32 v[38:39], v[28:29], v[22:23]
	v_pk_add_f32 v[26:27], v[26:27], v[36:37] neg_lo:[0,1] neg_hi:[0,1]
	v_pk_add_f32 v[28:29], v[28:29], v[38:39] neg_lo:[0,1] neg_hi:[0,1]
	v_pk_add_f32 v[26:27], v[30:31], v[26:27]
	v_pk_add_f32 v[22:23], v[22:23], v[28:29]
	v_pk_mul_f32 v[28:29], v[38:39], v[24:25]
	v_mov_b32_e32 v34, v32
	v_pk_mul_f32 v[30:31], v[36:37], v[28:29]
	v_mov_b32_e32 v42, v18
	v_pk_fma_f32 v[44:45], v[28:29], v[36:37], v[30:31] neg_lo:[0,0,1] neg_hi:[0,0,1]
	v_pk_add_f32 v[40:41], v[32:33], v[18:19]
	v_pk_fma_f32 v[44:45], v[28:29], v[26:27], v[44:45]
	v_cmp_neq_f32_e32 vcc, s97, v17
	v_pk_add_f32 v[46:47], v[30:31], v[44:45]
	v_mul_f32_e64 v3, |v9|, s84
	v_pk_add_f32 v[48:49], v[38:39], v[46:47] neg_lo:[0,1] neg_hi:[0,1]
	v_pk_add_f32 v[30:31], v[46:47], v[30:31] neg_lo:[0,1] neg_hi:[0,1]
	v_pk_add_f32 v[38:39], v[38:39], v[48:49] neg_lo:[0,1] neg_hi:[0,1]
	v_pk_add_f32 v[30:31], v[30:31], v[44:45] neg_lo:[0,1] neg_hi:[0,1]
	v_pk_add_f32 v[38:39], v[38:39], v[46:47] neg_lo:[0,1] neg_hi:[0,1]
	v_rndne_f32_e32 v7, v3
	v_pk_add_f32 v[22:23], v[22:23], v[38:39]
	s_nop 0
	v_pk_add_f32 v[22:23], v[30:31], v[22:23]
	s_nop 0
	v_pk_add_f32 v[30:31], v[48:49], v[22:23]
	s_nop 0
	v_pk_mul_f32 v[38:39], v[24:25], v[30:31]
	v_pk_add_f32 v[44:45], v[48:49], v[30:31] neg_lo:[0,1] neg_hi:[0,1]
	v_pk_mul_f32 v[46:47], v[36:37], v[38:39]
	v_pk_add_f32 v[22:23], v[22:23], v[44:45]
	v_pk_fma_f32 v[36:37], v[38:39], v[36:37], v[46:47] neg_lo:[0,0,1] neg_hi:[0,0,1]
	v_pk_add_f32 v[44:45], v[28:29], v[38:39]
	v_pk_fma_f32 v[26:27], v[38:39], v[26:27], v[36:37]
	v_pk_add_f32 v[28:29], v[44:45], v[28:29] neg_lo:[0,1] neg_hi:[0,1]
	v_pk_add_f32 v[36:37], v[46:47], v[26:27]
	v_pk_add_f32 v[28:29], v[38:39], v[28:29] neg_lo:[0,1] neg_hi:[0,1]
	v_pk_add_f32 v[38:39], v[36:37], v[46:47] neg_lo:[0,1] neg_hi:[0,1]
	v_pk_add_f32 v[46:47], v[30:31], v[36:37] neg_lo:[0,1] neg_hi:[0,1]
	v_pk_add_f32 v[26:27], v[38:39], v[26:27] neg_lo:[0,1] neg_hi:[0,1]
	v_pk_add_f32 v[30:31], v[30:31], v[46:47] neg_lo:[0,1] neg_hi:[0,1]
	v_mov_b32_e32 v39, v19
	v_pk_add_f32 v[30:31], v[30:31], v[36:37] neg_lo:[0,1] neg_hi:[0,1]
	v_mov_b32_e32 v36, v40
	v_pk_add_f32 v[22:23], v[22:23], v[30:31]
	v_mov_b32_e32 v37, v33
	v_pk_add_f32 v[22:23], v[26:27], v[22:23]
	s_nop 0
	v_pk_add_f32 v[22:23], v[46:47], v[22:23]
	v_mov_b32_e32 v47, v41
	v_pk_mul_f32 v[22:23], v[24:25], v[22:23]
	s_nop 0
	v_pk_add_f32 v[22:23], v[28:29], v[22:23]
	s_nop 0
	v_pk_add_f32 v[24:25], v[44:45], v[22:23]
	s_nop 0
	v_pk_add_f32 v[26:27], v[24:25], v[44:45] neg_lo:[0,1] neg_hi:[0,1]
	v_pk_mul_f32 v[30:31], v[24:25], v[24:25]
; __device__ __forceinline__ void norm_phase(const float* src, const float* gain, const float* shp, const float* scp, bf16* XN,
;                                            const float* w_in, const float* b_f, float* LF, LAS unsigned char* lds, int tid, int lane, int wave, int gw, int ngw) {
;     ...
;             for (int i = 0; i < 4; ++i) { const float z = ah[i] + al[i] + bias; lf[i] = fminf(z, 0.f) - log1pf(expf(-fabsf(z))); }
	v_pk_add_f32 v[22:23], v[22:23], v[26:27] neg_lo:[0,1] neg_hi:[0,1]
	v_pk_fma_f32 v[26:27], v[30:31], s[8:9], v[4:5] op_sel_hi:[1,0,0]
	v_ldexp_f32 v28, v24, 1
	v_ldexp_f32 v29, v25, 1
	v_pk_mul_f32 v[24:25], v[24:25], v[30:31]
	v_pk_fma_f32 v[26:27], v[30:31], v[26:27], s[12:13] op_sel_hi:[1,1,0]
	v_mov_b32_e32 v43, v29
	v_pk_mul_f32 v[24:25], v[24:25], v[26:27]
	v_ldexp_f32 v22, v22, 1
	v_pk_add_f32 v[26:27], v[28:29], v[24:25]
	v_ldexp_f32 v23, v23, 1
	v_pk_add_f32 v[28:29], v[26:27], v[28:29] neg_lo:[0,1] neg_hi:[0,1]
	v_mov_b32_e32 v35, v25
	v_pk_add_f32 v[24:25], v[24:25], v[28:29] neg_lo:[0,1] neg_hi:[0,1]
	v_pk_add_f32 v[30:31], v[34:35], v[42:43]
	v_pk_add_f32 v[28:29], v[22:23], v[24:25]
	v_mov_b32_e32 v24, v32
	v_mov_b32_e32 v22, v18
	v_pk_add_f32 v[34:35], v[24:25], v[22:23]
	v_mov_b32_e32 v22, v26
	v_mov_b32_e32 v24, v28
	v_pk_add_f32 v[22:23], v[22:23], v[24:25]
	v_pk_add_f32 v[24:25], v[26:27], v[28:29]
	v_pk_add_f32 v[22:23], v[30:31], v[22:23]
	v_mov_b32_e32 v38, v24
	v_pk_add_f32 v[30:31], v[40:41], v[24:25]
	v_pk_add_f32 v[42:43], v[36:37], v[38:39]
	v_mov_b32_e32 v44, v24
	v_mov_b32_e32 v45, v31
	v_mov_b32_e32 v46, v26
	v_pk_add_f32 v[36:37], v[42:43], v[36:37] neg_lo:[0,1] neg_hi:[0,1]
	v_pk_add_f32 v[44:45], v[44:45], v[46:47] neg_lo:[0,1] neg_hi:[0,1]
	v_pk_add_f32 v[42:43], v[40:41], v[32:33] neg_lo:[0,1] neg_hi:[0,1]
	v_pk_add_f32 v[38:39], v[38:39], v[36:37] neg_lo:[0,1] neg_hi:[0,1]
	v_mov_b32_e32 v46, v40
	v_mov_b32_e32 v47, v31
	v_mov_b32_e32 v33, v45
	v_mov_b32_e32 v37, v27
	v_pk_add_f32 v[26:27], v[24:25], v[26:27] neg_lo:[0,1] neg_hi:[0,1]
	v_pk_add_f32 v[32:33], v[46:47], v[32:33] neg_lo:[0,1] neg_hi:[0,1]
	v_pk_add_f32 v[42:43], v[18:19], v[42:43] neg_lo:[0,1] neg_hi:[0,1]
	v_pk_add_f32 v[22:23], v[22:23], v[36:37] neg_lo:[0,1] neg_hi:[0,1]
	v_pk_add_f32 v[26:27], v[28:29], v[26:27] neg_lo:[0,1] neg_hi:[0,1]
	v_mov_b32_e32 v19, v41
	v_mov_b32_e32 v29, v25
	v_pk_add_f32 v[22:23], v[34:35], v[22:23] neg_lo:[0,1] neg_hi:[0,1]
	v_pk_add_f32 v[18:19], v[18:19], v[32:33] neg_lo:[0,1] neg_hi:[0,1]
	v_pk_add_f32 v[24:25], v[28:29], v[44:45] neg_lo:[0,1] neg_hi:[0,1]
	v_pk_add_f32 v[32:33], v[38:39], v[22:23]
	v_pk_add_f32 v[28:29], v[24:25], v[18:19]
	v_mov_b32_e32 v25, v23
	v_pk_add_f32 v[22:23], v[42:43], v[24:25]
	v_mov_b32_e32 v19, v39
	v_pk_add_f32 v[22:23], v[22:23], v[18:19] neg_lo:[0,1] neg_hi:[0,1]
	v_mov_b32_e32 v24, v28
	v_mov_b32_e32 v25, v33
	v_pk_add_f32 v[24:25], v[24:25], v[22:23] neg_lo:[0,1] neg_hi:[0,1]
	v_pk_add_f32 v[22:23], v[26:27], v[22:23] neg_lo:[0,1] neg_hi:[0,1]
	v_pk_add_f32 v[18:19], v[18:19], v[24:25] neg_lo:[0,1] neg_hi:[0,1]
	s_nop 0
	v_pk_add_f32 v[18:19], v[22:23], v[18:19]
	v_pk_add_f32 v[22:23], v[32:33], v[28:29]
	s_nop 0
	v_pk_add_f32 v[24:25], v[30:31], v[22:23]
	s_nop 0
	v_pk_add_f32 v[26:27], v[24:25], v[30:31] neg_lo:[0,1] neg_hi:[0,1]
	s_nop 0
	v_pk_add_f32 v[22:23], v[22:23], v[26:27] neg_lo:[0,1] neg_hi:[0,1]
	s_nop 0
	v_pk_add_f32 v[18:19], v[18:19], v[22:23]
	v_fma_f32 v22, |v6|, s84, -v2
	v_rndne_f32_e32 v23, v2
	v_fma_f32 v22, |v6|, s82, v22
	v_sub_f32_e32 v2, v2, v23
	v_add_f32_e32 v2, v2, v22
	v_pk_add_f32 v[18:19], v[24:25], v[18:19]
	v_exp_f32_e32 v22, v2
	v_cvt_i32_f32_e32 v23, v23
	v_cndmask_b32_e32 v18, v214, v18, vcc
	v_cmp_neq_f32_e32 vcc, s97, v50
	v_min_f32_e32 v2, 0, v6
	v_cvt_i32_f32_e32 v24, v7
	v_cndmask_b32_e32 v19, v214, v19, vcc
	v_cmp_lt_f32_e64 vcc, |v50|, s69
	s_nop 1
	v_cndmask_b32_e32 v19, v19, v50, vcc
	v_cmp_lt_f32_e64 vcc, |v17|, s69
	s_nop 1
	v_cndmask_b32_e32 v18, v18, v17, vcc
	v_ldexp_f32 v17, v22, v23
	v_cmp_ngt_f32_e64 vcc, |v6|, s83
	v_pk_add_f32 v[0:1], v[0:1], v[18:19] neg_lo:[0,1] neg_hi:[0,1]
	s_nop 0
	v_cndmask_b32_e32 v17, 0, v17, vcc
	v_cmp_nlt_f32_e64 vcc, |v6|, s96
	s_nop 1
	v_cndmask_b32_e32 v17, v214, v17, vcc
	v_add_f32_e32 v18, 1.0, v17
	v_add_f32_e32 v6, -1.0, v18
	v_sub_f32_e32 v19, v6, v18
	v_add_f32_e32 v19, 1.0, v19
	v_sub_f32_e32 v6, v17, v6
	v_add_f32_e32 v19, v6, v19
	v_fma_f32 v6, |v9|, s84, -v3
	v_fma_f32 v6, |v9|, s82, v6
	v_sub_f32_e32 v3, v3, v7
	v_add_f32_e32 v3, v3, v6
	v_exp_f32_e32 v23, v3
	v_cvt_f64_f32_e32 v[6:7], v18
	v_frexp_exp_i32_f64_e32 v25, v[6:7]
	v_cmp_ngt_f32_e64 vcc, |v9|, s83
	v_ldexp_f32 v6, v23, v24
	v_min_f32_e32 v3, 0, v9
	v_cndmask_b32_e32 v6, 0, v6, vcc
	v_cmp_nlt_f32_e64 vcc, |v9|, s96
	v_frexp_mant_f32_e32 v22, v18
	s_nop 0
	v_cndmask_b32_e32 v9, v214, v6, vcc
	v_add_f32_e32 v23, 1.0, v9
	v_add_f32_e32 v6, -1.0, v23
	v_sub_f32_e32 v7, v6, v23
	v_add_f32_e32 v7, 1.0, v7
	v_sub_f32_e32 v6, v9, v6
	v_add_f32_e32 v24, v6, v7
	v_frexp_mant_f32_e32 v26, v23
	v_cvt_f64_f32_e32 v[6:7], v23
	v_frexp_exp_i32_f64_e32 v6, v[6:7]
	v_cmp_gt_f32_e32 vcc, s68, v26
	s_nop 1
	v_subbrev_co_u32_e32 v38, vcc, 0, v6, vcc
	v_cmp_gt_f32_e32 vcc, s68, v22
	s_nop 1
	v_subbrev_co_u32_e32 v39, vcc, 0, v25, vcc
	v_sub_u32_e32 v7, 0, v39
	v_ldexp_f32 v6, v18, v7
	v_ldexp_f32 v18, v19, v7
	v_sub_u32_e32 v19, 0, v38
	v_ldexp_f32 v7, v23, v19
	v_pk_add_f32 v[22:23], v[6:7], 1.0 op_sel_hi:[1,0]
	v_ldexp_f32 v19, v24, v19
	v_pk_add_f32 v[24:25], v[22:23], -1.0 op_sel_hi:[1,0]
	v_pk_add_f32 v[30:31], v[6:7], -1.0 op_sel_hi:[1,0]
	v_pk_add_f32 v[24:25], v[6:7], v[24:25] neg_lo:[0,1] neg_hi:[0,1]
	v_pk_add_f32 v[32:33], v[30:31], 1.0 op_sel_hi:[1,0]
	v_pk_add_f32 v[24:25], v[18:19], v[24:25]
	v_pk_add_f32 v[6:7], v[6:7], v[32:33] neg_lo:[0,1] neg_hi:[0,1]
	v_pk_add_f32 v[26:27], v[22:23], v[24:25]
	v_pk_add_f32 v[6:7], v[18:19], v[6:7]
	v_rcp_f32_e32 v28, v26
	v_rcp_f32_e32 v29, v27
	v_pk_add_f32 v[18:19], v[30:31], v[6:7]
	v_pk_add_f32 v[22:23], v[22:23], v[26:27] neg_lo:[0,1] neg_hi:[0,1]
; __device__ __forceinline__ void norm_phase(const float* src, const float* gain, const float* shp, const float* scp, bf16* XN,
;                                            const float* w_in, const float* b_f, float* LF, LAS unsigned char* lds, int tid, int lane, int wave, int gw, int ngw) {
;     ...
;         for (int grp = gw; grp < M / 8; grp += ngw) {
;     ...
;             for (int i = 0; i < 4; ++i) { const float z = ah[i] + al[i] + bias; lf[i] = fminf(z, 0.f) - log1pf(expf(-fabsf(z))); }
;             *(pg8::f32x4*)(LF + (size_t)(b * NH + fr) * SEQ + (row0 % SEQ) + 4 * fq) = lf;
	v_pk_add_f32 v[30:31], v[30:31], v[18:19] neg_lo:[0,1] neg_hi:[0,1]
	v_pk_add_f32 v[22:23], v[24:25], v[22:23]
	v_pk_mul_f32 v[24:25], v[18:19], v[28:29]
	v_pk_add_f32 v[6:7], v[6:7], v[30:31]
	v_pk_mul_f32 v[30:31], v[26:27], v[24:25]
	v_cmp_neq_f32_e32 vcc, s97, v17
	v_pk_fma_f32 v[32:33], v[24:25], v[26:27], v[30:31] neg_lo:[0,0,1] neg_hi:[0,0,1]
	s_nop 0
	v_pk_fma_f32 v[32:33], v[24:25], v[22:23], v[32:33]
	s_nop 0
	v_pk_add_f32 v[34:35], v[30:31], v[32:33]
	s_nop 0
	v_pk_add_f32 v[36:37], v[18:19], v[34:35] neg_lo:[0,1] neg_hi:[0,1]
	v_pk_add_f32 v[30:31], v[34:35], v[30:31] neg_lo:[0,1] neg_hi:[0,1]
	v_pk_add_f32 v[18:19], v[18:19], v[36:37] neg_lo:[0,1] neg_hi:[0,1]
	s_nop 0
	v_pk_add_f32 v[18:19], v[18:19], v[34:35] neg_lo:[0,1] neg_hi:[0,1]
	s_nop 0
	v_pk_add_f32 v[6:7], v[6:7], v[18:19]
	v_pk_add_f32 v[18:19], v[30:31], v[32:33] neg_lo:[0,1] neg_hi:[0,1]
	s_nop 0
	v_pk_add_f32 v[6:7], v[18:19], v[6:7]
	s_nop 0
	v_pk_add_f32 v[18:19], v[36:37], v[6:7]
	s_nop 0
	v_pk_mul_f32 v[30:31], v[28:29], v[18:19]
	s_nop 0
	v_pk_mul_f32 v[32:33], v[26:27], v[30:31]
	s_nop 0
	v_pk_fma_f32 v[26:27], v[30:31], v[26:27], v[32:33] neg_lo:[0,0,1] neg_hi:[0,0,1]
	s_nop 0
	v_pk_fma_f32 v[22:23], v[30:31], v[22:23], v[26:27]
	v_pk_add_f32 v[26:27], v[36:37], v[18:19] neg_lo:[0,1] neg_hi:[0,1]
	s_nop 0
	v_pk_add_f32 v[6:7], v[6:7], v[26:27]
	v_pk_add_f32 v[26:27], v[32:33], v[22:23]
	s_nop 0
	v_pk_add_f32 v[34:35], v[18:19], v[26:27] neg_lo:[0,1] neg_hi:[0,1]
	v_pk_add_f32 v[32:33], v[26:27], v[32:33] neg_lo:[0,1] neg_hi:[0,1]
	v_pk_add_f32 v[18:19], v[18:19], v[34:35] neg_lo:[0,1] neg_hi:[0,1]
	s_nop 0
	v_pk_add_f32 v[18:19], v[18:19], v[26:27] neg_lo:[0,1] neg_hi:[0,1]
	s_nop 0
	v_pk_add_f32 v[6:7], v[6:7], v[18:19]
	v_pk_add_f32 v[18:19], v[32:33], v[22:23] neg_lo:[0,1] neg_hi:[0,1]
	s_nop 0
	v_pk_add_f32 v[6:7], v[18:19], v[6:7]
	v_pk_add_f32 v[18:19], v[24:25], v[30:31]
	v_pk_add_f32 v[6:7], v[34:35], v[6:7]
	v_pk_add_f32 v[22:23], v[18:19], v[24:25] neg_lo:[0,1] neg_hi:[0,1]
	v_pk_mul_f32 v[6:7], v[28:29], v[6:7]
	v_pk_add_f32 v[22:23], v[30:31], v[22:23] neg_lo:[0,1] neg_hi:[0,1]
	v_cvt_f32_i32_e32 v25, v38
	v_pk_add_f32 v[6:7], v[22:23], v[6:7]
	v_cvt_f32_i32_e32 v24, v39
	v_pk_add_f32 v[22:23], v[18:19], v[6:7]
	v_pk_mul_f32 v[28:29], v[24:25], s[6:7] op_sel_hi:[1,0]
	v_pk_mul_f32 v[26:27], v[22:23], v[22:23]
	v_pk_add_f32 v[18:19], v[22:23], v[18:19] neg_lo:[0,1] neg_hi:[0,1]
	v_pk_fma_f32 v[4:5], v[26:27], s[8:9], v[4:5] op_sel_hi:[1,0,0]
	v_pk_add_f32 v[6:7], v[6:7], v[18:19] neg_lo:[0,1] neg_hi:[0,1]
	v_ldexp_f32 v18, v22, 1
	v_pk_fma_f32 v[4:5], v[26:27], v[4:5], s[12:13] op_sel_hi:[1,1,0]
	v_ldexp_f32 v19, v23, 1
	v_pk_mul_f32 v[22:23], v[22:23], v[26:27]
	v_pk_fma_f32 v[30:31], v[24:25], s[6:7], v[28:29] op_sel_hi:[1,0,1] neg_lo:[0,0,1] neg_hi:[0,0,1]
	v_pk_mul_f32 v[4:5], v[22:23], v[4:5]
	v_mov_b32_e32 v33, v19
	v_pk_add_f32 v[22:23], v[18:19], v[4:5]
	v_ldexp_f32 v6, v6, 1
	v_pk_add_f32 v[18:19], v[22:23], v[18:19] neg_lo:[0,1] neg_hi:[0,1]
	v_pk_fma_f32 v[24:25], v[24:25], s[14:15], v[30:31] op_sel_hi:[1,0,1]
	v_ldexp_f32 v7, v7, 1
	v_mov_b32_e32 v27, v5
	v_pk_add_f32 v[4:5], v[4:5], v[18:19] neg_lo:[0,1] neg_hi:[0,1]
	v_mov_b32_e32 v26, v28
	v_mov_b32_e32 v32, v24
	v_pk_add_f32 v[18:19], v[6:7], v[4:5]
	v_mov_b32_e32 v4, v28
	v_mov_b32_e32 v6, v24
	v_pk_add_f32 v[26:27], v[26:27], v[32:33]
	v_pk_add_f32 v[32:33], v[4:5], v[6:7]
	v_mov_b32_e32 v6, v22
	v_mov_b32_e32 v4, v18
	v_pk_add_f32 v[30:31], v[28:29], v[24:25]
	v_pk_add_f32 v[4:5], v[6:7], v[4:5]
	v_pk_add_f32 v[6:7], v[22:23], v[18:19]
	v_mov_b32_e32 v34, v30
	v_mov_b32_e32 v35, v29
	v_mov_b32_e32 v36, v6
	v_mov_b32_e32 v37, v25
	v_pk_add_f32 v[4:5], v[26:27], v[4:5]
	v_pk_add_f32 v[26:27], v[30:31], v[6:7]
	v_pk_add_f32 v[38:39], v[34:35], v[36:37]
	v_mov_b32_e32 v40, v6
	v_mov_b32_e32 v41, v27
	v_mov_b32_e32 v42, v22
	v_mov_b32_e32 v43, v31
	v_pk_add_f32 v[34:35], v[38:39], v[34:35] neg_lo:[0,1] neg_hi:[0,1]
	v_pk_add_f32 v[40:41], v[40:41], v[42:43] neg_lo:[0,1] neg_hi:[0,1]
	v_pk_add_f32 v[38:39], v[30:31], v[28:29] neg_lo:[0,1] neg_hi:[0,1]
	v_pk_add_f32 v[36:37], v[36:37], v[34:35] neg_lo:[0,1] neg_hi:[0,1]
	v_mov_b32_e32 v42, v30
	v_mov_b32_e32 v43, v27
	v_mov_b32_e32 v29, v41
	v_mov_b32_e32 v35, v23
	v_pk_add_f32 v[22:23], v[6:7], v[22:23] neg_lo:[0,1] neg_hi:[0,1]
	v_pk_add_f32 v[28:29], v[42:43], v[28:29] neg_lo:[0,1] neg_hi:[0,1]
	v_pk_add_f32 v[38:39], v[24:25], v[38:39] neg_lo:[0,1] neg_hi:[0,1]
	v_pk_add_f32 v[4:5], v[4:5], v[34:35] neg_lo:[0,1] neg_hi:[0,1]
	v_pk_add_f32 v[22:23], v[18:19], v[22:23] neg_lo:[0,1] neg_hi:[0,1]
	v_mov_b32_e32 v25, v31
	v_mov_b32_e32 v19, v7
	v_pk_add_f32 v[4:5], v[32:33], v[4:5] neg_lo:[0,1] neg_hi:[0,1]
	v_pk_add_f32 v[24:25], v[24:25], v[28:29] neg_lo:[0,1] neg_hi:[0,1]
	v_pk_add_f32 v[6:7], v[18:19], v[40:41] neg_lo:[0,1] neg_hi:[0,1]
	v_pk_add_f32 v[28:29], v[36:37], v[4:5]
	v_pk_add_f32 v[18:19], v[6:7], v[24:25]
	v_mov_b32_e32 v7, v5
	v_pk_add_f32 v[4:5], v[38:39], v[6:7]
	v_mov_b32_e32 v25, v37
	v_pk_add_f32 v[4:5], v[4:5], v[24:25] neg_lo:[0,1] neg_hi:[0,1]
	v_mov_b32_e32 v6, v18
	v_mov_b32_e32 v7, v29
	v_pk_add_f32 v[6:7], v[6:7], v[4:5] neg_lo:[0,1] neg_hi:[0,1]
	v_pk_add_f32 v[4:5], v[22:23], v[4:5] neg_lo:[0,1] neg_hi:[0,1]
	v_pk_add_f32 v[6:7], v[24:25], v[6:7] neg_lo:[0,1] neg_hi:[0,1]
	s_ashr_i32 s8, s2, 31
	v_pk_add_f32 v[4:5], v[4:5], v[6:7]
	v_pk_add_f32 v[6:7], v[28:29], v[18:19]
	s_lshr_b32 s8, s8, 23
	v_pk_add_f32 v[18:19], v[26:27], v[6:7]
	s_add_i32 s8, s2, s8
	v_pk_add_f32 v[22:23], v[18:19], v[26:27] neg_lo:[0,1] neg_hi:[0,1]
	s_ashr_i32 s8, s8, 9
	v_pk_add_f32 v[6:7], v[6:7], v[22:23] neg_lo:[0,1] neg_hi:[0,1]
	s_nop 0
	v_pk_add_f32 v[4:5], v[4:5], v[6:7]
	s_nop 0
	v_pk_add_f32 v[4:5], v[18:19], v[4:5]
	s_nop 0
	v_cndmask_b32_e32 v4, v214, v4, vcc
	v_cmp_neq_f32_e32 vcc, s97, v9
	s_nop 1
	v_cndmask_b32_e32 v5, v214, v5, vcc
	v_cmp_lt_f32_e64 vcc, |v9|, s69
	s_nop 1
	v_cndmask_b32_e32 v5, v5, v9, vcc
	v_cmp_lt_f32_e64 vcc, |v17|, s69
	s_nop 1
	v_cndmask_b32_e32 v4, v4, v17, vcc
	v_pk_add_f32 v[2:3], v[2:3], v[4:5] neg_lo:[0,1] neg_hi:[0,1]
	v_lshl_or_b32 v4, s8, 4, v20
	s_bfe_i32 s8, s2, 0x1001c
	s_lshr_b32 s8, s8, 20
	s_add_i32 s8, s7, s8
	v_ashrrev_i32_e32 v5, 31, v4
	s_and_b32 s8, s8, 0xfffff000
	v_lshlrev_b64 v[4:5], 14, v[4:5]
	s_sub_i32 s14, s7, s8
	v_lshl_add_u64 v[4:5], s[16:17], 0, v[4:5]
	s_ashr_i32 s15, s14, 31
	v_lshl_add_u64 v[4:5], s[14:15], 2, v[4:5]
	s_add_i32 s2, s2, s13
	v_lshl_add_u64 v[4:5], v[4:5], 0, v[194:195]
	s_cmpk_gt_i32 s2, 0x7ff
	global_store_dwordx4 v[4:5], v[0:3], off
	s_cbranch_scc0 .LBB0_565

; #define LAS __attribute__((address_space(3)))
; __device__ __forceinline__ void shiftw_mfma(const float* mod, unsigned char* ws, float* SW, LAS unsigned char* lds, int tid, int lane, int gw, int ngw) {
;     ...
;         const bf16* wp = Wt + (size_t)(g0 * 16 + fr) * DM + 8 * fq;
;         const LAS bf16* sp = S + (mat * 8 + (fr & 7)) * DM + 8 * fq;
;         pg8::f32x4 acc = {0.f, 0.f, 0.f, 0.f};
; #pragma unroll 8
;         for (int kk = 0; kk < DM / 32; ++kk) { const pg8::bf16x8 wf = *(const pg8::bf16x8*)(wp + 32 * kk); pg8::bf16x8 sf = *(const LAS pg8::bf16x8*)(sp + 32 * kk);
;             if (fr >= 8) sf = (pg8::bf16x8){0, 0, 0, 0, 0, 0, 0, 0};
;             acc = __builtin_amdgcn_mfma_f32_16x16x32_bf16(wf, sf, acc, 0, 0, 0); }
.LBB0_572:
	s_waitcnt lgkmcnt(0)
	v_mov_b32_e32 v188, v7
	global_load_dwordx4 v[64:67], v[8:9], off offset:0
	global_load_dwordx4 v[68:71], v[8:9], off offset:64
	global_load_dwordx4 v[72:75], v[8:9], off offset:128
	global_load_dwordx4 v[76:79], v[8:9], off offset:192
	global_load_dwordx4 v[80:83], v[8:9], off offset:256
	global_load_dwordx4 v[84:87], v[8:9], off offset:320
	global_load_dwordx4 v[88:91], v[8:9], off offset:384
	global_load_dwordx4 v[92:95], v[8:9], off offset:448
	global_load_dwordx4 v[96:99], v[8:9], off offset:512
	global_load_dwordx4 v[100:103], v[8:9], off offset:576
	global_load_dwordx4 v[104:107], v[8:9], off offset:640
	global_load_dwordx4 v[108:111], v[8:9], off offset:704
	global_load_dwordx4 v[112:115], v[8:9], off offset:768
	global_load_dwordx4 v[116:119], v[8:9], off offset:832
	global_load_dwordx4 v[120:123], v[8:9], off offset:896
	global_load_dwordx4 v[124:127], v[8:9], off offset:960
	ds_read_b128 v[172:175], v188
	s_mov_b64 s[22:23], 0x400
	s_mov_b32 s20, 0
	s_waitcnt lgkmcnt(0)
	v_cndmask_b32_e64 v175, v175, 0, vcc
	v_cndmask_b32_e64 v174, v174, 0, vcc
	v_cndmask_b32_e64 v173, v173, 0, vcc
	v_cndmask_b32_e64 v172, v172, 0, vcc
; #define LAS __attribute__((address_space(3)))
; __device__ __forceinline__ void shiftw_mfma(const float* mod, unsigned char* ws, float* SW, LAS unsigned char* lds, int tid, int lane, int gw, int ngw) {
;     ...
;     for (int g = gw; g < 1408; g += ngw) {
;         const int mat = g < 512 ? 0 : (g < 896 ? 1 : 2), g0 = g - (mat == 0 ? 0 : (mat == 1 ? 512 : 896)), N = mat == 1 ? 3 * DM : FF;
;         const bf16* Wt = (const bf16*)(ws + (mat == 0 ? WS_WUP0 : (mat == 1 ? WS_WCIN : WS_WUP1)));
;         float* sw = SW + (mat == 0 ? SW_UP0 : (mat == 1 ? SW_CIN : SW_UP1));
;         const bf16* wp = Wt + (size_t)(g0 * 16 + fr) * DM + 8 * fq;
;         const LAS bf16* sp = S + (mat * 8 + (fr & 7)) * DM + 8 * fq;
;         pg8::f32x4 acc = {0.f, 0.f, 0.f, 0.f};
; #pragma unroll 8
;         for (int kk = 0; kk < DM / 32; ++kk) { const pg8::bf16x8 wf = *(const pg8::bf16x8*)(wp + 32 * kk); pg8::bf16x8 sf = *(const LAS pg8::bf16x8*)(sp + 32 * kk);
;             if (fr >= 8) sf = (pg8::bf16x8){0, 0, 0, 0, 0, 0, 0, 0};
;             acc = __builtin_amdgcn_mfma_f32_16x16x32_bf16(wf, sf, acc, 0, 0, 0); }
;         pg8::f32x4 r;
; #pragma unroll
;         for (int i = 0; i < 4; ++i) r[i] = acc[i] + __shfl_xor(acc[i], 4);
;         if (fr < 4) *(pg8::f32x4*)(sw + (size_t)fr * N + g0 * 16 + 4 * fq) = r;
;     }
.Lshiftw_loop:
	ds_read_b128 v[176:179], v188 offset:64
	s_waitcnt vmcnt(15)
	s_nop 0
	v_mfma_f32_16x16x32_bf16 v[0:3], v[64:67], v[172:175], v[0:3]
	s_waitcnt lgkmcnt(0)
	v_cndmask_b32_e64 v179, v179, 0, vcc
	v_cndmask_b32_e64 v178, v178, 0, vcc
	v_cndmask_b32_e64 v177, v177, 0, vcc
	v_cndmask_b32_e64 v176, v176, 0, vcc
	ds_read_b128 v[172:175], v188 offset:128
	s_waitcnt vmcnt(14)
	s_nop 0
	v_mfma_f32_16x16x32_bf16 v[0:3], v[68:71], v[176:179], v[0:3]
	s_waitcnt lgkmcnt(0)
	v_cndmask_b32_e64 v175, v175, 0, vcc
	v_cndmask_b32_e64 v174, v174, 0, vcc
	v_cndmask_b32_e64 v173, v173, 0, vcc
	v_cndmask_b32_e64 v172, v172, 0, vcc
	global_load_dwordx4 v[64:67], v[8:9], off offset:1024
	ds_read_b128 v[176:179], v188 offset:192
	s_waitcnt vmcnt(14)
	s_nop 0
	v_mfma_f32_16x16x32_bf16 v[0:3], v[72:75], v[172:175], v[0:3]
	s_waitcnt lgkmcnt(0)
	v_cndmask_b32_e64 v179, v179, 0, vcc
	v_cndmask_b32_e64 v178, v178, 0, vcc
	v_cndmask_b32_e64 v177, v177, 0, vcc
	v_cndmask_b32_e64 v176, v176, 0, vcc
	global_load_dwordx4 v[68:71], v[8:9], off offset:1088
	ds_read_b128 v[172:175], v188 offset:256
	s_waitcnt vmcnt(14)
	s_nop 0
	v_mfma_f32_16x16x32_bf16 v[0:3], v[76:79], v[176:179], v[0:3]
	s_waitcnt lgkmcnt(0)
	v_cndmask_b32_e64 v175, v175, 0, vcc
	v_cndmask_b32_e64 v174, v174, 0, vcc
	v_cndmask_b32_e64 v173, v173, 0, vcc
	v_cndmask_b32_e64 v172, v172, 0, vcc
	global_load_dwordx4 v[72:75], v[8:9], off offset:1152
	ds_read_b128 v[176:179], v188 offset:320
	s_waitcnt vmcnt(14)
	s_nop 0
	v_mfma_f32_16x16x32_bf16 v[0:3], v[80:83], v[172:175], v[0:3]
	s_waitcnt lgkmcnt(0)
	v_cndmask_b32_e64 v179, v179, 0, vcc
	v_cndmask_b32_e64 v178, v178, 0, vcc
	v_cndmask_b32_e64 v177, v177, 0, vcc
	v_cndmask_b32_e64 v176, v176, 0, vcc
	global_load_dwordx4 v[76:79], v[8:9], off offset:1216
	ds_read_b128 v[172:175], v188 offset:384
	s_waitcnt vmcnt(14)
	s_nop 0
	v_mfma_f32_16x16x32_bf16 v[0:3], v[84:87], v[176:179], v[0:3]
	s_waitcnt lgkmcnt(0)
	v_cndmask_b32_e64 v175, v175, 0, vcc
	v_cndmask_b32_e64 v174, v174, 0, vcc
	v_cndmask_b32_e64 v173, v173, 0, vcc
	v_cndmask_b32_e64 v172, v172, 0, vcc
	global_load_dwordx4 v[80:83], v[8:9], off offset:1280
	ds_read_b128 v[176:179], v188 offset:448
	s_waitcnt vmcnt(14)
	s_nop 0
	v_mfma_f32_16x16x32_bf16 v[0:3], v[88:91], v[172:175], v[0:3]
	s_waitcnt lgkmcnt(0)
	v_cndmask_b32_e64 v179, v179, 0, vcc
	v_cndmask_b32_e64 v178, v178, 0, vcc
	v_cndmask_b32_e64 v177, v177, 0, vcc
	v_cndmask_b32_e64 v176, v176, 0, vcc
	global_load_dwordx4 v[84:87], v[8:9], off offset:1344
	ds_read_b128 v[172:175], v188 offset:512
	s_waitcnt vmcnt(14)
	s_nop 0
	v_mfma_f32_16x16x32_bf16 v[0:3], v[92:95], v[176:179], v[0:3]
	s_waitcnt lgkmcnt(0)
	v_cndmask_b32_e64 v175, v175, 0, vcc
	v_cndmask_b32_e64 v174, v174, 0, vcc
	v_cndmask_b32_e64 v173, v173, 0, vcc
	v_cndmask_b32_e64 v172, v172, 0, vcc
	global_load_dwordx4 v[88:91], v[8:9], off offset:1408
	ds_read_b128 v[176:179], v188 offset:576
	s_waitcnt vmcnt(14)
	s_nop 0
	v_mfma_f32_16x16x32_bf16 v[0:3], v[96:99], v[172:175], v[0:3]
	s_waitcnt lgkmcnt(0)
	v_cndmask_b32_e64 v179, v179, 0, vcc
	v_cndmask_b32_e64 v178, v178, 0, vcc
	v_cndmask_b32_e64 v177, v177, 0, vcc
	v_cndmask_b32_e64 v176, v176, 0, vcc
	global_load_dwordx4 v[92:95], v[8:9], off offset:1472
	ds_read_b128 v[172:175], v188 offset:640
	s_waitcnt vmcnt(14)
	s_nop 0
	v_mfma_f32_16x16x32_bf16 v[0:3], v[100:103], v[176:179], v[0:3]
	s_waitcnt lgkmcnt(0)
	v_cndmask_b32_e64 v175, v175, 0, vcc
	v_cndmask_b32_e64 v174, v174, 0, vcc
	v_cndmask_b32_e64 v173, v173, 0, vcc
	v_cndmask_b32_e64 v172, v172, 0, vcc
	global_load_dwordx4 v[96:99], v[8:9], off offset:1536
	ds_read_b128 v[176:179], v188 offset:704
	s_waitcnt vmcnt(14)
	s_nop 0
	v_mfma_f32_16x16x32_bf16 v[0:3], v[104:107], v[172:175], v[0:3]
	s_waitcnt lgkmcnt(0)
	v_cndmask_b32_e64 v179, v179, 0, vcc
	v_cndmask_b32_e64 v178, v178, 0, vcc
	v_cndmask_b32_e64 v177, v177, 0, vcc
	v_cndmask_b32_e64 v176, v176, 0, vcc
	global_load_dwordx4 v[100:103], v[8:9], off offset:1600
	ds_read_b128 v[172:175], v188 offset:768
	s_waitcnt vmcnt(14)
	s_nop 0
	v_mfma_f32_16x16x32_bf16 v[0:3], v[108:111], v[176:179], v[0:3]
	s_waitcnt lgkmcnt(0)
	v_cndmask_b32_e64 v175, v175, 0, vcc
	v_cndmask_b32_e64 v174, v174, 0, vcc
	v_cndmask_b32_e64 v173, v173, 0, vcc
	v_cndmask_b32_e64 v172, v172, 0, vcc
	global_load_dwordx4 v[104:107], v[8:9], off offset:1664
	ds_read_b128 v[176:179], v188 offset:832
	s_waitcnt vmcnt(14)
	s_nop 0
	v_mfma_f32_16x16x32_bf16 v[0:3], v[112:115], v[172:175], v[0:3]
	s_waitcnt lgkmcnt(0)
	v_cndmask_b32_e64 v179, v179, 0, vcc
	v_cndmask_b32_e64 v178, v178, 0, vcc
	v_cndmask_b32_e64 v177, v177, 0, vcc
	v_cndmask_b32_e64 v176, v176, 0, vcc
	global_load_dwordx4 v[108:111], v[8:9], off offset:1728
	ds_read_b128 v[172:175], v188 offset:896
	s_waitcnt vmcnt(14)
	s_nop 0
	v_mfma_f32_16x16x32_bf16 v[0:3], v[116:119], v[176:179], v[0:3]
	s_waitcnt lgkmcnt(0)
	v_cndmask_b32_e64 v175, v175, 0, vcc
	v_cndmask_b32_e64 v174, v174, 0, vcc
	v_cndmask_b32_e64 v173, v173, 0, vcc
	v_cndmask_b32_e64 v172, v172, 0, vcc
	global_load_dwordx4 v[112:115], v[8:9], off offset:1792
	ds_read_b128 v[176:179], v188 offset:960
	s_waitcnt vmcnt(14)
	s_nop 0
	v_mfma_f32_16x16x32_bf16 v[0:3], v[120:123], v[172:175], v[0:3]
	s_waitcnt lgkmcnt(0)
	v_cndmask_b32_e64 v179, v179, 0, vcc
	v_cndmask_b32_e64 v178, v178, 0, vcc
	v_cndmask_b32_e64 v177, v177, 0, vcc
	v_cndmask_b32_e64 v176, v176, 0, vcc
	global_load_dwordx4 v[116:119], v[8:9], off offset:1856
	ds_read_b128 v[172:175], v188 offset:1024
	s_waitcnt vmcnt(14)
	s_nop 0
	v_mfma_f32_16x16x32_bf16 v[0:3], v[124:127], v[176:179], v[0:3]
	s_waitcnt lgkmcnt(0)
	v_cndmask_b32_e64 v175, v175, 0, vcc
	v_cndmask_b32_e64 v174, v174, 0, vcc
	v_cndmask_b32_e64 v173, v173, 0, vcc
	v_cndmask_b32_e64 v172, v172, 0, vcc
	global_load_dwordx4 v[120:123], v[8:9], off offset:1920
	global_load_dwordx4 v[124:127], v[8:9], off offset:1984
	v_add_u32_e32 v188, 0x400, v188
	v_lshl_add_u64 v[8:9], v[8:9], 0, s[22:23]
	s_add_i32 s20, s20, 1
	s_cmp_lg_u32 s20, 4
	s_cbranch_scc1 .Lshiftw_loop
	s_nop 1
	s_nop 6
	ds_bpermute_b32 v8, v13, v0
	ds_bpermute_b32 v9, v13, v1
	ds_bpermute_b32 v10, v13, v2
	ds_bpermute_b32 v11, v13, v3
	s_and_saveexec_b64 s[20:21], s[40:41]
	s_cbranch_execz .LBB0_570
	s_and_b64 s[22:23], s[14:15], exec
	s_mov_b32 s2, 0xe000
	s_cselect_b32 s2, 0x8000, s2
	s_and_b64 s[18:19], s[18:19], exec
	s_cselect_b32 s2, s2, 0
	s_lshl_b32 s2, s2, 2
	s_add_u32 s18, s12, s2
	s_addc_u32 s19, s24, 0
	s_and_b64 s[14:15], s[14:15], exec
	s_cselect_b32 s2, 0x1800, s62
	v_mul_u32_u24_e32 v7, s2, v20
	v_lshlrev_b32_e32 v194, 2, v7
	s_waitcnt lgkmcnt(2)
	v_pk_add_f32 v[0:1], v[0:1], v[8:9]
	v_lshl_add_u64 v[8:9], s[18:19], 0, v[194:195]
	s_ashr_i32 s17, s16, 31
	v_lshl_add_u64 v[8:9], s[16:17], 2, v[8:9]
	v_mov_b32_e32 v7, v195
	s_waitcnt lgkmcnt(0)
	v_pk_add_f32 v[2:3], v[2:3], v[10:11]
	v_lshl_add_u64 v[8:9], v[8:9], 0, v[6:7]
	global_store_dwordx4 v[8:9], v[0:3], off
	s_branch .LBB0_570
